# v13 + dropped the unused per-XCD release atomic + LayerNorm phase: row loads issued back to back, gamma/beta/shift/scale loads hoisted into one batch
# baseline (speedup 1.0000x reference)
.LBB0_61:
	s_or_b64 exec, exec, s[28:29]
	v_add_u32_e32 v0, 0xffffe000, v66
	v_lshrrev_b32_e32 v0, 10, v0
	s_movk_i32 s2, 0x1fff
	v_add_u32_e32 v0, 1, v0
	v_cmp_lt_i32_e32 vcc, s2, v66
	v_readlane_b32 s24, v232, 27
	s_mul_i32 s2, s24, 9
	v_cndmask_b32_e32 v0, 0, v0, vcc
	v_readlane_b32 s25, v232, 28
	v_add_u32_e32 v2, s2, v0
	v_mov_b64_e32 v[0:1], s[94:95]
	v_mad_i64_i32 v[0:1], s[24:25], v2, s79, v[0:1]
	s_mov_b64 s[24:25], 0x6023000
	s_nop 0
	v_lshl_add_u64 v[84:85], v[0:1], 0, s[24:25]
	s_mov_b64 s[24:25], 0x6024000
	v_lshl_add_u64 v[86:87], v[0:1], 0, s[24:25]
	v_mov_b32_e32 v77, v33
	v_mov_b32_e32 v79, v33
	v_mov_b32_e32 v81, v33
	global_load_dwordx4 v[124:127], v[68:69], off
	global_load_dwordx4 v[140:143], v[70:71], off
	v_lshl_add_u64 v[176:177], v[84:85], 0, v[32:33]
	v_lshl_add_u64 v[192:193], v[86:87], 0, v[32:33]
	global_load_dwordx4 v[176:179], v[176:177], off
	s_nop 0
	global_load_dwordx4 v[192:195], v[192:193], off
	s_nop 0
	global_load_dwordx4 v[128:131], v[68:69], off offset:1024
	global_load_dwordx4 v[144:147], v[70:71], off offset:1024
	v_lshl_add_u64 v[180:181], v[84:85], 0, v[76:77]
	v_lshl_add_u64 v[196:197], v[86:87], 0, v[76:77]
	global_load_dwordx4 v[180:183], v[180:181], off
	s_nop 0
	global_load_dwordx4 v[196:199], v[196:197], off
	s_nop 0
	global_load_dwordx4 v[132:135], v[68:69], off offset:2048
	global_load_dwordx4 v[148:151], v[70:71], off offset:2048
	v_lshl_add_u64 v[184:185], v[84:85], 0, v[78:79]
	v_lshl_add_u64 v[200:201], v[86:87], 0, v[78:79]
	global_load_dwordx4 v[184:187], v[184:185], off
	s_nop 0
	global_load_dwordx4 v[200:203], v[200:201], off
	s_nop 0
	global_load_dwordx4 v[136:139], v[68:69], off offset:3072
	global_load_dwordx4 v[152:155], v[70:71], off offset:3072
	v_lshl_add_u64 v[188:189], v[84:85], 0, v[80:81]
	v_lshl_add_u64 v[204:205], v[86:87], 0, v[80:81]
	global_load_dwordx4 v[188:191], v[188:189], off
	s_nop 0
	global_load_dwordx4 v[204:207], v[204:205], off
	s_nop 0
	v_pk_mul_f32 v[82:83], v[82:83], v[28:29] op_sel_hi:[1,0]
	v_pk_mul_f32 v[100:101], v[100:101], v[28:29] op_sel_hi:[1,0]
	v_pk_mul_f32 v[88:89], v[88:89], v[12:13] op_sel_hi:[1,0]
	v_pk_mul_f32 v[90:91], v[90:91], v[12:13] op_sel_hi:[1,0]
	s_movk_i32 s2, 0xf000
	v_pk_mul_f32 v[46:47], v[46:47], v[12:13] op_sel_hi:[1,0]
	v_pk_mul_f32 v[44:45], v[44:45], v[12:13] op_sel_hi:[1,0]
	v_pk_mul_f32 v[62:63], v[62:63], v[28:29] op_sel_hi:[1,0]
	v_pk_mul_f32 v[64:65], v[64:65], v[28:29] op_sel_hi:[1,0]
	v_pk_mul_f32 v[36:37], v[36:37], v[30:31] op_sel_hi:[1,0]
	v_pk_mul_f32 v[40:41], v[40:41], v[12:13] op_sel_hi:[1,0]
	v_pk_mul_f32 v[24:25], v[24:25], v[34:35] op_sel_hi:[1,0]
	v_pk_mul_f32 v[26:27], v[26:27], v[34:35] op_sel_hi:[1,0]
	v_pk_mul_f32 v[14:15], v[14:15], v[30:31] op_sel_hi:[1,0]
	v_pk_mul_f32 v[22:23], v[22:23], v[30:31] op_sel_hi:[1,0]
	v_pk_mul_f32 v[8:9], v[8:9], v[30:31] op_sel_hi:[1,0]
	v_pk_mul_f32 v[10:11], v[10:11], v[30:31] op_sel_hi:[1,0]
	v_readlane_b32 s24, v233, 46
	v_readlane_b32 s25, v233, 47
	v_add_u32_e32 v66, s70, v66
	s_waitcnt vmcnt(14)
	v_pk_fma_f32 v[82:83], v[82:83], v[124:125], v[140:141]
	s_waitcnt vmcnt(12)
	v_pk_add_f32 v[116:117], v[192:193], 1.0 op_sel_hi:[1,0]
	v_pk_add_f32 v[118:119], v[194:195], 1.0 op_sel_hi:[1,0]
	v_pk_fma_f32 v[82:83], v[82:83], v[116:117], v[176:177]
	v_pk_fma_f32 v[88:89], v[88:89], v[124:125], v[140:141]
	v_cvt_pk_bf16_f32 v120, v82, v83
	v_pk_fma_f32 v[82:83], v[100:101], v[126:127], v[142:143]
	v_pk_fma_f32 v[90:91], v[90:91], v[126:127], v[142:143]
	v_pk_fma_f32 v[82:83], v[82:83], v[118:119], v[178:179]
	v_pk_fma_f32 v[88:89], v[88:89], v[116:117], v[176:177]
	v_cvt_pk_bf16_f32 v121, v82, v83
	v_add_co_u32_e32 v82, vcc, s2, v72
	v_pk_fma_f32 v[90:91], v[90:91], v[118:119], v[178:179]
	s_nop 0
	v_addc_co_u32_e32 v83, vcc, -1, v73, vcc
	v_cvt_pk_bf16_f32 v88, v88, v89
	v_cvt_pk_bf16_f32 v89, v90, v91
	global_store_dwordx2 v[82:83], v[88:89], off offset:-1536
	v_pk_mul_f32 v[88:89], v[96:97], v[34:35] op_sel_hi:[1,0]
	v_pk_mul_f32 v[90:91], v[98:99], v[34:35] op_sel_hi:[1,0]
	v_pk_fma_f32 v[88:89], v[88:89], v[124:125], v[140:141]
	v_pk_fma_f32 v[90:91], v[90:91], v[126:127], v[142:143]
	v_pk_fma_f32 v[88:89], v[88:89], v[116:117], v[176:177]
	v_pk_fma_f32 v[90:91], v[90:91], v[118:119], v[178:179]
	v_cvt_pk_bf16_f32 v88, v88, v89
	v_cvt_pk_bf16_f32 v89, v90, v91
	global_store_dwordx2 v[72:73], v[88:89], off offset:-3584
	v_pk_mul_f32 v[88:89], v[92:93], v[30:31] op_sel_hi:[1,0]
	v_pk_mul_f32 v[90:91], v[94:95], v[30:31] op_sel_hi:[1,0]
	v_pk_fma_f32 v[0:1], v[88:89], v[124:125], v[140:141]
	v_pk_fma_f32 v[2:3], v[90:91], v[126:127], v[142:143]
	v_pk_fma_f32 v[0:1], v[0:1], v[116:117], v[176:177]
	v_pk_fma_f32 v[2:3], v[2:3], v[118:119], v[178:179]
	v_cvt_pk_bf16_f32 v0, v0, v1
	v_cvt_pk_bf16_f32 v1, v2, v3
	global_store_dwordx2 v[82:83], v[120:121], off offset:-3584
	global_store_dwordx2 v[72:73], v[0:1], off offset:-1536
	v_cmp_lt_i32_e32 vcc, s51, v66
	s_or_b64 s[20:21], vcc, s[20:21]
	s_waitcnt vmcnt(14)
	v_pk_fma_f32 v[46:47], v[46:47], v[128:129], v[144:145]
	s_waitcnt vmcnt(12)
	v_pk_add_f32 v[92:93], v[196:197], 1.0 op_sel_hi:[1,0]
	v_pk_add_f32 v[94:95], v[198:199], 1.0 op_sel_hi:[1,0]
	v_pk_fma_f32 v[44:45], v[44:45], v[130:131], v[146:147]
	v_pk_fma_f32 v[46:47], v[46:47], v[92:93], v[180:181]
	v_pk_fma_f32 v[44:45], v[44:45], v[94:95], v[182:183]
	v_cvt_pk_bf16_f32 v46, v46, v47
	v_cvt_pk_bf16_f32 v47, v44, v45
	global_store_dwordx2 v[82:83], v[46:47], off offset:-1024
	v_pk_mul_f32 v[44:45], v[58:59], v[34:35] op_sel_hi:[1,0]
	v_pk_mul_f32 v[46:47], v[60:61], v[34:35] op_sel_hi:[1,0]
	v_pk_fma_f32 v[44:45], v[44:45], v[128:129], v[144:145]
	v_pk_fma_f32 v[46:47], v[46:47], v[130:131], v[146:147]
	v_pk_fma_f32 v[44:45], v[44:45], v[92:93], v[180:181]
	v_pk_fma_f32 v[46:47], v[46:47], v[94:95], v[182:183]
	v_cvt_pk_bf16_f32 v44, v44, v45
	v_cvt_pk_bf16_f32 v45, v46, v47
	global_store_dwordx2 v[72:73], v[44:45], off offset:-3072
	v_pk_mul_f32 v[44:45], v[48:49], v[30:31] op_sel_hi:[1,0]
	v_pk_fma_f32 v[62:63], v[62:63], v[128:129], v[144:145]
	v_pk_fma_f32 v[64:65], v[64:65], v[130:131], v[146:147]
	v_pk_fma_f32 v[0:1], v[36:37], v[128:129], v[144:145]
	v_pk_fma_f32 v[2:3], v[44:45], v[130:131], v[146:147]
	v_pk_fma_f32 v[62:63], v[62:63], v[92:93], v[180:181]
	v_pk_fma_f32 v[64:65], v[64:65], v[94:95], v[182:183]
	v_pk_fma_f32 v[0:1], v[0:1], v[92:93], v[180:181]
	v_pk_fma_f32 v[2:3], v[2:3], v[94:95], v[182:183]
	v_cvt_pk_bf16_f32 v62, v62, v63
	v_cvt_pk_bf16_f32 v63, v64, v65
	v_cvt_pk_bf16_f32 v0, v0, v1
	v_cvt_pk_bf16_f32 v1, v2, v3
	global_store_dwordx2 v[82:83], v[62:63], off offset:-3072
	global_store_dwordx2 v[72:73], v[0:1], off offset:-1024
	v_pk_mul_f32 v[36:37], v[54:55], v[28:29] op_sel_hi:[1,0]
	v_pk_mul_f32 v[48:49], v[56:57], v[28:29] op_sel_hi:[1,0]
	s_waitcnt vmcnt(14)
	v_pk_fma_f32 v[36:37], v[36:37], v[132:133], v[148:149]
	v_pk_fma_f32 v[48:49], v[48:49], v[134:135], v[150:151]
	s_waitcnt vmcnt(12)
	v_pk_add_f32 v[54:55], v[200:201], 1.0 op_sel_hi:[1,0]
	v_pk_add_f32 v[56:57], v[202:203], 1.0 op_sel_hi:[1,0]
	v_pk_fma_f32 v[36:37], v[36:37], v[54:55], v[184:185]
	v_pk_fma_f32 v[48:49], v[48:49], v[56:57], v[186:187]
	v_cvt_pk_bf16_f32 v36, v36, v37
	v_cvt_pk_bf16_f32 v37, v48, v49
	global_store_dwordx2 v[82:83], v[36:37], off offset:-2560
	v_pk_mul_f32 v[36:37], v[42:43], v[12:13] op_sel_hi:[1,0]
	v_pk_fma_f32 v[40:41], v[40:41], v[134:135], v[150:151]
	v_pk_fma_f32 v[36:37], v[36:37], v[132:133], v[148:149]
	v_pk_fma_f32 v[24:25], v[24:25], v[132:133], v[148:149]
	v_pk_fma_f32 v[26:27], v[26:27], v[134:135], v[150:151]
	v_pk_fma_f32 v[0:1], v[14:15], v[132:133], v[148:149]
	v_pk_fma_f32 v[2:3], v[22:23], v[134:135], v[150:151]
	v_pk_fma_f32 v[36:37], v[36:37], v[54:55], v[184:185]
	v_pk_fma_f32 v[40:41], v[40:41], v[56:57], v[186:187]
	v_pk_fma_f32 v[24:25], v[24:25], v[54:55], v[184:185]
	v_pk_fma_f32 v[26:27], v[26:27], v[56:57], v[186:187]
	v_pk_fma_f32 v[0:1], v[0:1], v[54:55], v[184:185]
	v_pk_fma_f32 v[2:3], v[2:3], v[56:57], v[186:187]
	v_cvt_pk_bf16_f32 v36, v36, v37
	v_cvt_pk_bf16_f32 v37, v40, v41
	v_cvt_pk_bf16_f32 v24, v24, v25
	v_cvt_pk_bf16_f32 v25, v26, v27
	v_cvt_pk_bf16_f32 v0, v0, v1
	v_cvt_pk_bf16_f32 v1, v2, v3
	global_store_dwordx2 v[82:83], v[36:37], off offset:-512
	global_store_dwordx2 v[72:73], v[24:25], off offset:-2560
	global_store_dwordx2 v[72:73], v[0:1], off offset:-512
	v_pk_mul_f32 v[14:15], v[50:51], v[28:29] op_sel_hi:[1,0]
	v_pk_mul_f32 v[26:27], v[52:53], v[28:29] op_sel_hi:[1,0]
	s_waitcnt vmcnt(14)
	v_pk_fma_f32 v[14:15], v[14:15], v[136:137], v[152:153]
	v_pk_fma_f32 v[26:27], v[26:27], v[138:139], v[154:155]
	s_waitcnt vmcnt(12)
	v_pk_add_f32 v[28:29], v[204:205], 1.0 op_sel_hi:[1,0]
	v_pk_add_f32 v[36:37], v[206:207], 1.0 op_sel_hi:[1,0]
	v_pk_fma_f32 v[14:15], v[14:15], v[28:29], v[188:189]
	v_pk_fma_f32 v[26:27], v[26:27], v[36:37], v[190:191]
	v_cvt_pk_bf16_f32 v14, v14, v15
	v_cvt_pk_bf16_f32 v15, v26, v27
	global_store_dwordx2 v[82:83], v[14:15], off offset:-2048
	v_pk_mul_f32 v[14:15], v[16:17], v[12:13] op_sel_hi:[1,0]
	v_pk_mul_f32 v[12:13], v[38:39], v[12:13] op_sel_hi:[1,0]
	v_pk_fma_f32 v[14:15], v[14:15], v[136:137], v[152:153]
	v_pk_fma_f32 v[12:13], v[12:13], v[138:139], v[154:155]
	v_pk_fma_f32 v[14:15], v[14:15], v[28:29], v[188:189]
	v_pk_fma_f32 v[12:13], v[12:13], v[36:37], v[190:191]
	v_cvt_pk_bf16_f32 v14, v14, v15
	v_cvt_pk_bf16_f32 v15, v12, v13
	global_store_dwordx2 v[72:73], v[14:15], off offset:-4096
	v_pk_mul_f32 v[12:13], v[18:19], v[34:35] op_sel_hi:[1,0]
	v_pk_mul_f32 v[14:15], v[20:21], v[34:35] op_sel_hi:[1,0]
	v_pk_fma_f32 v[12:13], v[12:13], v[136:137], v[152:153]
	v_pk_fma_f32 v[14:15], v[14:15], v[138:139], v[154:155]
	v_pk_fma_f32 v[0:1], v[8:9], v[136:137], v[152:153]
	v_pk_fma_f32 v[2:3], v[10:11], v[138:139], v[154:155]
	v_pk_fma_f32 v[12:13], v[12:13], v[28:29], v[188:189]
	v_pk_fma_f32 v[14:15], v[14:15], v[36:37], v[190:191]
	v_pk_fma_f32 v[0:1], v[0:1], v[28:29], v[188:189]
	v_pk_fma_f32 v[2:3], v[2:3], v[36:37], v[190:191]
	v_cvt_pk_bf16_f32 v12, v12, v13
	v_cvt_pk_bf16_f32 v13, v14, v15
	v_cvt_pk_bf16_f32 v0, v0, v1
	v_cvt_pk_bf16_f32 v1, v2, v3
	global_store_dwordx2 v[72:73], v[12:13], off offset:-2048
	global_store_dwordx2 v[72:73], v[0:1], off
	v_lshl_add_u64 v[72:73], v[72:73], 0, s[24:25]
	v_readlane_b32 s24, v233, 50
	v_readlane_b32 s25, v233, 51
	s_nop 1
	v_lshl_add_u64 v[74:75], v[74:75], 0, s[24:25]
	s_andn2_b64 exec, exec, s[20:21]
	s_cbranch_execz .LBB0_64
.LBB0_62:
	v_add_co_u32_e32 v0, vcc, 0xffffd000, v74
	s_mov_b32 s2, 0x3727c5ac
	s_nop 0
	v_addc_co_u32_e32 v1, vcc, -1, v75, vcc
	global_load_dwordx4 v[62:65], v[0:1], off offset:-3072
	global_load_dwordx4 v[58:61], v[0:1], off offset:-2048
	global_load_dwordx4 v[54:57], v[0:1], off offset:-1024
	global_load_dwordx4 v[50:53], v[0:1], off
	v_add_co_u32_e32 v0, vcc, 0xffffe000, v74
	v_addc_co_u32_e32 v1, vcc, -1, v75, vcc
	global_load_dwordx4 v[46:49], v[0:1], off offset:-3072
	global_load_dwordx4 v[42:45], v[0:1], off offset:-2048
	global_load_dwordx4 v[38:41], v[0:1], off offset:-1024
	global_load_dwordx4 v[16:19], v[0:1], off
	v_add_co_u32_e32 v0, vcc, 0xfffff000, v74
	v_addc_co_u32_e32 v1, vcc, -1, v75, vcc
	global_load_dwordx4 v[34:37], v[0:1], off offset:-3072
	global_load_dwordx4 v[28:31], v[0:1], off offset:-2048
	global_load_dwordx4 v[24:27], v[0:1], off offset:-1024
	global_load_dwordx4 v[20:23], v[74:75], off offset:-4096
	global_load_dwordx4 v[12:15], v[74:75], off offset:-3072
	global_load_dwordx4 v[8:11], v[74:75], off offset:-2048
	global_load_dwordx4 v[4:7], v[74:75], off offset:-1024
	s_nop 0
	global_load_dwordx4 v[0:3], v[74:75], off
	s_waitcnt vmcnt(15)
	v_mov_b32_e32 v82, v62
	s_waitcnt vmcnt(14)
	v_mov_b32_e32 v83, v58
	v_mov_b32_e32 v84, v63
	v_mov_b32_e32 v85, v59
	v_pk_add_f32 v[82:83], v[82:83], v[84:85]
	v_mov_b32_e32 v84, v64
	v_mov_b32_e32 v85, v60
	v_pk_add_f32 v[82:83], v[84:85], v[82:83]
	v_mov_b32_e32 v84, v65
	v_mov_b32_e32 v85, v61
	v_pk_add_f32 v[82:83], v[84:85], v[82:83]
	s_waitcnt vmcnt(13)
	v_mov_b32_e32 v84, v55
	v_add_f32_e32 v67, 0, v82
	v_add_f32_e32 v67, v67, v83
	v_mov_b32_e32 v82, v54
	s_waitcnt vmcnt(12)
	v_mov_b32_e32 v83, v50
	v_mov_b32_e32 v85, v51
	v_pk_add_f32 v[82:83], v[82:83], v[84:85]
	v_mov_b32_e32 v84, v56
	v_mov_b32_e32 v85, v52
	v_pk_add_f32 v[82:83], v[84:85], v[82:83]
	v_mov_b32_e32 v84, v57
	v_mov_b32_e32 v85, v53
	v_pk_add_f32 v[82:83], v[84:85], v[82:83]
	s_waitcnt vmcnt(11)
	v_mov_b32_e32 v84, v47
	v_add_f32_e32 v67, v67, v82
	v_add_f32_e32 v67, v67, v83
	v_mov_b32_e32 v82, v46
	s_waitcnt vmcnt(10)
	v_mov_b32_e32 v83, v42
	v_mov_b32_e32 v85, v43
	v_pk_add_f32 v[82:83], v[82:83], v[84:85]
	v_mov_b32_e32 v84, v48
	v_mov_b32_e32 v85, v44
	v_pk_add_f32 v[82:83], v[84:85], v[82:83]
	v_mov_b32_e32 v84, v49
	v_mov_b32_e32 v85, v45
	v_pk_add_f32 v[82:83], v[84:85], v[82:83]
	s_waitcnt vmcnt(9)
	v_mov_b32_e32 v84, v39
	v_add_f32_e32 v77, 0, v82
	v_add_f32_e32 v77, v77, v83
	v_mov_b32_e32 v82, v38
	s_waitcnt vmcnt(8)
	v_mov_b32_e32 v83, v16
	v_mov_b32_e32 v85, v17
	v_pk_add_f32 v[82:83], v[82:83], v[84:85]
	v_mov_b32_e32 v84, v40
	v_mov_b32_e32 v85, v18
	v_pk_add_f32 v[82:83], v[84:85], v[82:83]
	v_mov_b32_e32 v84, v41
	v_mov_b32_e32 v85, v19
	v_pk_add_f32 v[82:83], v[84:85], v[82:83]
	s_waitcnt vmcnt(7)
	v_mov_b32_e32 v84, v35
	v_add_f32_e32 v77, v77, v82
	v_add_f32_e32 v77, v77, v83
	v_mov_b32_e32 v82, v34
	s_waitcnt vmcnt(6)
	v_mov_b32_e32 v83, v28
	v_mov_b32_e32 v85, v29
	v_pk_add_f32 v[82:83], v[82:83], v[84:85]
	v_mov_b32_e32 v84, v36
	v_mov_b32_e32 v85, v30
	v_pk_add_f32 v[82:83], v[84:85], v[82:83]
	v_mov_b32_e32 v84, v37
	v_mov_b32_e32 v85, v31
	v_pk_add_f32 v[82:83], v[84:85], v[82:83]
	s_waitcnt vmcnt(5)
	v_mov_b32_e32 v84, v25
	v_add_f32_e32 v79, 0, v82
	v_add_f32_e32 v79, v79, v83
	v_mov_b32_e32 v82, v24
	s_waitcnt vmcnt(4)
	v_mov_b32_e32 v83, v20
	v_mov_b32_e32 v85, v21
	v_pk_add_f32 v[82:83], v[82:83], v[84:85]
	v_mov_b32_e32 v84, v26
	v_mov_b32_e32 v85, v22
	v_pk_add_f32 v[82:83], v[84:85], v[82:83]
	v_mov_b32_e32 v84, v27
	v_mov_b32_e32 v85, v23
	v_pk_add_f32 v[82:83], v[84:85], v[82:83]
	s_waitcnt vmcnt(3)
	v_mov_b32_e32 v84, v13
	v_add_f32_e32 v79, v79, v82
	v_add_f32_e32 v79, v79, v83
	v_mov_b32_e32 v82, v12
	s_waitcnt vmcnt(2)
	v_mov_b32_e32 v83, v8
	v_mov_b32_e32 v85, v9
	v_pk_add_f32 v[82:83], v[82:83], v[84:85]
	v_mov_b32_e32 v84, v14
	v_mov_b32_e32 v85, v10
	v_pk_add_f32 v[82:83], v[84:85], v[82:83]
	v_mov_b32_e32 v84, v15
	v_mov_b32_e32 v85, v11
	v_pk_add_f32 v[82:83], v[84:85], v[82:83]
	s_waitcnt vmcnt(1)
	v_mov_b32_e32 v84, v5
	v_add_f32_e32 v81, 0, v82
	v_add_f32_e32 v81, v81, v83
	v_mov_b32_e32 v82, v4
	s_waitcnt vmcnt(0)
	v_mov_b32_e32 v83, v0
	v_mov_b32_e32 v85, v1
	v_pk_add_f32 v[82:83], v[82:83], v[84:85]
	v_mov_b32_e32 v84, v6
	v_mov_b32_e32 v85, v2
	v_pk_add_f32 v[82:83], v[84:85], v[82:83]
	v_mov_b32_e32 v84, v7
	v_mov_b32_e32 v85, v3
	v_pk_add_f32 v[82:83], v[84:85], v[82:83]
	s_nop 0
	v_add_f32_e32 v81, v81, v82
	ds_bpermute_b32 v82, v105, v67
	v_add_f32_e32 v81, v81, v83
	s_waitcnt lgkmcnt(0)
	v_add_f32_e32 v67, v67, v82
	ds_bpermute_b32 v82, v105, v77
	s_waitcnt lgkmcnt(0)
	v_add_f32_e32 v77, v77, v82
	ds_bpermute_b32 v82, v105, v79
	s_waitcnt lgkmcnt(0)
	v_add_f32_e32 v79, v79, v82
	ds_bpermute_b32 v82, v105, v81
	s_waitcnt lgkmcnt(0)
	v_add_f32_e32 v81, v81, v82
	ds_bpermute_b32 v82, v106, v67
	s_waitcnt lgkmcnt(0)
	v_add_f32_e32 v67, v67, v82
	ds_bpermute_b32 v82, v106, v77
	s_waitcnt lgkmcnt(0)
	v_add_f32_e32 v77, v77, v82
	ds_bpermute_b32 v82, v106, v79
	s_waitcnt lgkmcnt(0)
	v_add_f32_e32 v79, v79, v82
	ds_bpermute_b32 v82, v106, v81
	s_waitcnt lgkmcnt(0)
	v_add_f32_e32 v81, v81, v82
	ds_bpermute_b32 v82, v107, v67
	s_waitcnt lgkmcnt(0)
	v_add_f32_e32 v67, v67, v82
	ds_bpermute_b32 v82, v107, v77
	s_waitcnt lgkmcnt(0)
	v_add_f32_e32 v77, v77, v82
	ds_bpermute_b32 v82, v107, v79
	s_waitcnt lgkmcnt(0)
	v_add_f32_e32 v79, v79, v82
	ds_bpermute_b32 v82, v107, v81
	s_waitcnt lgkmcnt(0)
	v_add_f32_e32 v81, v81, v82
	ds_bpermute_b32 v82, v108, v67
	s_waitcnt lgkmcnt(0)
	v_add_f32_e32 v67, v67, v82
	ds_bpermute_b32 v82, v108, v77
	s_waitcnt lgkmcnt(0)
	v_add_f32_e32 v77, v77, v82
	ds_bpermute_b32 v82, v108, v79
	s_waitcnt lgkmcnt(0)
	v_add_f32_e32 v79, v79, v82
	ds_bpermute_b32 v82, v108, v81
	s_waitcnt lgkmcnt(0)
	v_add_f32_e32 v81, v81, v82
	ds_bpermute_b32 v82, v109, v67
	s_waitcnt lgkmcnt(0)
	v_add_f32_e32 v67, v67, v82
	ds_bpermute_b32 v82, v109, v77
	s_waitcnt lgkmcnt(0)
	v_add_f32_e32 v77, v77, v82
	ds_bpermute_b32 v82, v109, v79
	s_waitcnt lgkmcnt(0)
	v_add_f32_e32 v79, v79, v82
	ds_bpermute_b32 v82, v109, v81
	s_waitcnt lgkmcnt(0)
	v_add_f32_e32 v81, v81, v82
	ds_bpermute_b32 v82, v110, v67
	s_waitcnt lgkmcnt(0)
	v_add_f32_e32 v67, v67, v82
	ds_bpermute_b32 v82, v110, v77
	v_mul_f32_e32 v84, 0x3a800000, v67
	v_pk_add_f32 v[100:101], v[64:65], v[84:85] op_sel_hi:[1,0] neg_lo:[0,1] neg_hi:[0,1]
	v_pk_add_f32 v[64:65], v[60:61], v[84:85] op_sel_hi:[1,0] neg_lo:[0,1] neg_hi:[0,1]
	v_pk_add_f32 v[54:55], v[54:55], v[84:85] op_sel_hi:[1,0] neg_lo:[0,1] neg_hi:[0,1]
	s_waitcnt lgkmcnt(0)
	v_add_f32_e32 v77, v77, v82
	ds_bpermute_b32 v82, v110, v79
	v_mul_f32_e32 v86, 0x3a800000, v77
	v_pk_add_f32 v[88:89], v[46:47], v[86:87] op_sel_hi:[1,0] neg_lo:[0,1] neg_hi:[0,1]
	v_pk_add_f32 v[90:91], v[48:49], v[86:87] op_sel_hi:[1,0] neg_lo:[0,1] neg_hi:[0,1]
	v_mov_b32_e32 v46, v88
	s_waitcnt lgkmcnt(0)
	v_add_f32_e32 v79, v79, v82
	ds_bpermute_b32 v82, v110, v81
	v_mov_b32_e32 v48, v90
	v_mov_b32_e32 v49, v100
	v_pk_add_f32 v[44:45], v[44:45], v[86:87] op_sel_hi:[1,0] neg_lo:[0,1] neg_hi:[0,1]
	v_pk_add_f32 v[56:57], v[56:57], v[84:85] op_sel_hi:[1,0] neg_lo:[0,1] neg_hi:[0,1]
	s_waitcnt lgkmcnt(0)
	v_add_f32_e32 v81, v81, v82
	v_pk_add_f32 v[82:83], v[62:63], v[84:85] op_sel_hi:[1,0] neg_lo:[0,1] neg_hi:[0,1]
	v_pk_add_f32 v[62:63], v[58:59], v[84:85] op_sel_hi:[1,0] neg_lo:[0,1] neg_hi:[0,1]
	v_mov_b32_e32 v58, v89
	v_mov_b32_e32 v59, v83
	v_mov_b32_e32 v47, v82
	v_pk_mul_f32 v[58:59], v[58:59], v[58:59]
	v_pk_add_f32 v[40:41], v[40:41], v[86:87] op_sel_hi:[1,0] neg_lo:[0,1] neg_hi:[0,1]
	v_pk_fma_f32 v[58:59], v[46:47], v[46:47], v[58:59]
	v_pk_add_f32 v[46:47], v[42:43], v[86:87] op_sel_hi:[1,0] neg_lo:[0,1] neg_hi:[0,1]
	v_pk_add_f32 v[42:43], v[38:39], v[86:87] op_sel_hi:[1,0] neg_lo:[0,1] neg_hi:[0,1]
	v_pk_fma_f32 v[38:39], v[48:49], v[48:49], v[58:59]
	v_mov_b32_e32 v48, v91
	v_mov_b32_e32 v49, v101
	v_pk_fma_f32 v[38:39], v[48:49], v[48:49], v[38:39]
	v_mov_b32_e32 v48, v46
	v_mov_b32_e32 v49, v62
	v_pk_fma_f32 v[38:39], v[48:49], v[48:49], v[38:39]
	v_mov_b32_e32 v48, v47
	v_mov_b32_e32 v49, v63
	v_pk_fma_f32 v[38:39], v[48:49], v[48:49], v[38:39]
	v_mov_b32_e32 v48, v44
	v_mov_b32_e32 v49, v64
	v_pk_fma_f32 v[38:39], v[48:49], v[48:49], v[38:39]
	v_mov_b32_e32 v48, v45
	v_mov_b32_e32 v49, v65
	v_pk_fma_f32 v[38:39], v[48:49], v[48:49], v[38:39]
	v_mov_b32_e32 v48, v42
	v_mov_b32_e32 v49, v54
	v_pk_fma_f32 v[38:39], v[48:49], v[48:49], v[38:39]
	v_mov_b32_e32 v48, v43
	v_mov_b32_e32 v49, v55
	v_pk_add_f32 v[50:51], v[50:51], v[84:85] op_sel_hi:[1,0] neg_lo:[0,1] neg_hi:[0,1]
	v_pk_add_f32 v[16:17], v[16:17], v[86:87] op_sel_hi:[1,0] neg_lo:[0,1] neg_hi:[0,1]
	v_pk_fma_f32 v[38:39], v[48:49], v[48:49], v[38:39]
	v_mov_b32_e32 v48, v40
	v_mov_b32_e32 v49, v56
	v_pk_mul_f32 v[112:113], v[50:51], v[50:51]
	v_pk_mul_f32 v[116:117], v[16:17], v[16:17]
	v_pk_fma_f32 v[38:39], v[48:49], v[48:49], v[38:39]
	v_mov_b32_e32 v48, v41
	v_mov_b32_e32 v49, v57
	v_mul_f32_e32 v102, 0x3a800000, v79
	v_mul_f32_e32 v104, 0x3a800000, v81
	v_pk_fma_f32 v[38:39], v[48:49], v[48:49], v[38:39]
	v_mov_b32_e32 v48, v116
	v_mov_b32_e32 v49, v112
	v_pk_add_f32 v[96:97], v[34:35], v[102:103] op_sel_hi:[1,0] neg_lo:[0,1] neg_hi:[0,1]
	v_pk_add_f32 v[92:93], v[12:13], v[104:105] op_sel_hi:[1,0] neg_lo:[0,1] neg_hi:[0,1]
	v_pk_add_f32 v[118:119], v[48:49], v[38:39]
	v_pk_add_f32 v[38:39], v[18:19], v[86:87] op_sel_hi:[1,0] neg_lo:[0,1] neg_hi:[0,1]
	v_pk_add_f32 v[18:19], v[20:21], v[102:103] op_sel_hi:[1,0] neg_lo:[0,1] neg_hi:[0,1]
	v_pk_add_f32 v[20:21], v[22:23], v[102:103] op_sel_hi:[1,0] neg_lo:[0,1] neg_hi:[0,1]
	v_mov_b32_e32 v22, v93
	v_mov_b32_e32 v23, v97
	v_pk_add_f32 v[98:99], v[36:37], v[102:103] op_sel_hi:[1,0] neg_lo:[0,1] neg_hi:[0,1]
	v_mov_b32_e32 v12, v92
	v_mov_b32_e32 v13, v96
	v_pk_mul_f32 v[22:23], v[22:23], v[22:23]
	v_pk_add_f32 v[94:95], v[14:15], v[104:105] op_sel_hi:[1,0] neg_lo:[0,1] neg_hi:[0,1]
	v_pk_add_f32 v[58:59], v[28:29], v[102:103] op_sel_hi:[1,0] neg_lo:[0,1] neg_hi:[0,1]
	v_pk_fma_f32 v[12:13], v[12:13], v[12:13], v[22:23]
	v_mov_b32_e32 v28, v94
	v_mov_b32_e32 v29, v98
	v_pk_add_f32 v[36:37], v[8:9], v[104:105] op_sel_hi:[1,0] neg_lo:[0,1] neg_hi:[0,1]
	v_pk_add_f32 v[14:15], v[4:5], v[104:105] op_sel_hi:[1,0] neg_lo:[0,1] neg_hi:[0,1]
	v_pk_add_f32 v[22:23], v[6:7], v[104:105] op_sel_hi:[1,0] neg_lo:[0,1] neg_hi:[0,1]
	v_pk_fma_f32 v[4:5], v[28:29], v[28:29], v[12:13]
	v_mov_b32_e32 v6, v95
	v_mov_b32_e32 v7, v99
	v_pk_fma_f32 v[4:5], v[6:7], v[6:7], v[4:5]
	v_mov_b32_e32 v6, v36
	v_mov_b32_e32 v7, v58
	v_pk_add_f32 v[60:61], v[30:31], v[102:103] op_sel_hi:[1,0] neg_lo:[0,1] neg_hi:[0,1]
	v_pk_add_f32 v[48:49], v[10:11], v[104:105] op_sel_hi:[1,0] neg_lo:[0,1] neg_hi:[0,1]
	v_pk_fma_f32 v[4:5], v[6:7], v[6:7], v[4:5]
	v_mov_b32_e32 v6, v37
	v_mov_b32_e32 v7, v59
	v_pk_fma_f32 v[4:5], v[6:7], v[6:7], v[4:5]
	v_mov_b32_e32 v6, v48
	v_mov_b32_e32 v7, v60
	v_pk_add_f32 v[24:25], v[24:25], v[102:103] op_sel_hi:[1,0] neg_lo:[0,1] neg_hi:[0,1]
	v_pk_fma_f32 v[4:5], v[6:7], v[6:7], v[4:5]
	v_mov_b32_e32 v6, v49
	v_mov_b32_e32 v7, v61
	v_pk_fma_f32 v[4:5], v[6:7], v[6:7], v[4:5]
	v_mov_b32_e32 v6, v14
	v_mov_b32_e32 v7, v24
	v_pk_add_f32 v[26:27], v[26:27], v[102:103] op_sel_hi:[1,0] neg_lo:[0,1] neg_hi:[0,1]
	v_pk_fma_f32 v[4:5], v[6:7], v[6:7], v[4:5]
	v_mov_b32_e32 v6, v15
	v_mov_b32_e32 v7, v25
	v_pk_add_f32 v[8:9], v[0:1], v[104:105] op_sel_hi:[1,0] neg_lo:[0,1] neg_hi:[0,1]
	v_pk_fma_f32 v[4:5], v[6:7], v[6:7], v[4:5]
	v_mov_b32_e32 v6, v22
	v_mov_b32_e32 v7, v26
	v_pk_add_f32 v[52:53], v[52:53], v[84:85] op_sel_hi:[1,0] neg_lo:[0,1] neg_hi:[0,1]
	v_pk_mul_f32 v[34:35], v[18:19], v[18:19]
	v_pk_mul_f32 v[0:1], v[8:9], v[8:9]
	v_pk_fma_f32 v[4:5], v[6:7], v[6:7], v[4:5]
	v_mov_b32_e32 v6, v23
	v_mov_b32_e32 v7, v27
	v_pk_mul_f32 v[114:115], v[52:53], v[52:53]
	v_pk_mul_f32 v[120:121], v[38:39], v[38:39]
	v_pk_fma_f32 v[4:5], v[6:7], v[6:7], v[4:5]
	v_mov_b32_e32 v6, v0
	v_mov_b32_e32 v7, v34
	v_mov_b32_e32 v112, v117
	v_pk_add_f32 v[4:5], v[6:7], v[4:5]
	v_pk_add_f32 v[6:7], v[112:113], v[118:119]
	v_mov_b32_e32 v12, v120
	v_mov_b32_e32 v13, v114
	v_pk_add_f32 v[6:7], v[12:13], v[6:7]
	v_mov_b32_e32 v114, v121
	v_pk_add_f32 v[6:7], v[114:115], v[6:7]
	ds_bpermute_b32 v13, v105, v7
	ds_bpermute_b32 v12, v105, v6
	v_mov_b64_e32 v[112:113], s[2:3]
	s_mov_b32 s2, 0x3a800000
	v_pk_add_f32 v[10:11], v[2:3], v[104:105] op_sel_hi:[1,0] neg_lo:[0,1] neg_hi:[0,1]
	v_pk_mul_f32 v[30:31], v[20:21], v[20:21]
	s_waitcnt lgkmcnt(0)
	v_pk_add_f32 v[6:7], v[6:7], v[12:13]
	ds_bpermute_b32 v13, v106, v7
	ds_bpermute_b32 v12, v106, v6
	v_pk_mul_f32 v[2:3], v[10:11], v[10:11]
	v_mov_b32_e32 v34, v1
	s_waitcnt lgkmcnt(0)
	v_pk_add_f32 v[6:7], v[6:7], v[12:13]
	ds_bpermute_b32 v13, v107, v7
	ds_bpermute_b32 v12, v107, v6
	s_waitcnt lgkmcnt(0)
	v_pk_add_f32 v[6:7], v[6:7], v[12:13]
	ds_bpermute_b32 v13, v108, v7
	ds_bpermute_b32 v12, v108, v6
	s_waitcnt lgkmcnt(0)
	v_pk_add_f32 v[6:7], v[6:7], v[12:13]
	ds_bpermute_b32 v13, v109, v7
	ds_bpermute_b32 v12, v109, v6
	s_waitcnt lgkmcnt(0)
	v_pk_add_f32 v[6:7], v[6:7], v[12:13]
	ds_bpermute_b32 v13, v110, v7
	ds_bpermute_b32 v12, v110, v6
	s_waitcnt lgkmcnt(0)
	v_pk_add_f32 v[6:7], v[6:7], v[12:13]
	s_nop 0
	v_pk_fma_f32 v[6:7], v[6:7], s[2:3], v[112:113] op_sel_hi:[1,0,0]
	s_nop 0
	v_mul_f32_e32 v0, 0x4b800000, v7
	v_cmp_gt_f32_e64 s[46:47], s26, v7
	v_cmp_gt_f32_e32 vcc, s26, v6
	s_nop 0
	v_cndmask_b32_e64 v0, v7, v0, s[46:47]
	v_rsq_f32_e32 v0, v0
	s_nop 0
	v_mul_f32_e32 v7, 0x45800000, v0
	v_cndmask_b32_e64 v28, v0, v7, s[46:47]
	v_mul_f32_e32 v0, 0x4b800000, v6
	v_cndmask_b32_e32 v0, v6, v0, vcc
	v_rsq_f32_e32 v0, v0
	s_nop 0
	v_mul_f32_e32 v6, 0x45800000, v0
	v_cndmask_b32_e32 v12, v0, v6, vcc
	v_pk_add_f32 v[0:1], v[34:35], v[4:5]
	v_mov_b32_e32 v4, v2
	v_mov_b32_e32 v5, v30
	v_pk_add_f32 v[0:1], v[4:5], v[0:1]
	v_mov_b32_e32 v30, v3
	v_pk_add_f32 v[0:1], v[30:31], v[0:1]
	ds_bpermute_b32 v3, v105, v1
	ds_bpermute_b32 v2, v105, v0
	s_waitcnt lgkmcnt(0)
	v_pk_add_f32 v[0:1], v[0:1], v[2:3]
	ds_bpermute_b32 v3, v106, v1
	ds_bpermute_b32 v2, v106, v0
	s_waitcnt lgkmcnt(0)
	v_pk_add_f32 v[0:1], v[0:1], v[2:3]
	ds_bpermute_b32 v3, v107, v1
	ds_bpermute_b32 v2, v107, v0
	s_waitcnt lgkmcnt(0)
	v_pk_add_f32 v[0:1], v[0:1], v[2:3]
	ds_bpermute_b32 v3, v108, v1
	ds_bpermute_b32 v2, v108, v0
	s_waitcnt lgkmcnt(0)
	v_pk_add_f32 v[0:1], v[0:1], v[2:3]
	ds_bpermute_b32 v3, v109, v1
	ds_bpermute_b32 v2, v109, v0
	s_waitcnt lgkmcnt(0)
	v_pk_add_f32 v[0:1], v[0:1], v[2:3]
	ds_bpermute_b32 v3, v110, v1
	ds_bpermute_b32 v2, v110, v0
	s_waitcnt lgkmcnt(0)
	v_pk_add_f32 v[0:1], v[0:1], v[2:3]
	s_nop 0
	v_pk_fma_f32 v[0:1], v[0:1], s[2:3], v[112:113] op_sel_hi:[1,0,0]
	s_nop 0
	v_mul_f32_e32 v2, 0x4b800000, v1
	v_cmp_gt_f32_e64 s[46:47], s26, v1
	v_cmp_gt_f32_e32 vcc, s26, v0
	s_nop 0
	v_cndmask_b32_e64 v1, v1, v2, s[46:47]
	v_rsq_f32_e32 v1, v1
	s_nop 0
	v_mul_f32_e32 v2, 0x45800000, v1
	v_cndmask_b32_e64 v34, v1, v2, s[46:47]
	v_mul_f32_e32 v1, 0x4b800000, v0
	v_cndmask_b32_e32 v0, v0, v1, vcc
	v_rsq_f32_e32 v0, v0
	s_nop 0
	v_mul_f32_e32 v1, 0x45800000, v0
	v_cndmask_b32_e32 v30, v0, v1, vcc
	s_and_saveexec_b64 s[28:29], s[38:39]
	s_cbranch_execz .LBB0_61
	v_cndmask_b32_e64 v0, v104, v102, s[44:45]
	v_cndmask_b32_e64 v1, v30, v34, s[44:45]
	v_add_u32_e32 v2, v103, v66
	v_readlane_b32 s24, v235, 38
	v_cndmask_b32_e64 v0, v0, v86, s[42:43]
	v_cndmask_b32_e64 v1, v1, v12, s[42:43]
	v_ashrrev_i32_e32 v3, 31, v2
	v_readlane_b32 s25, v235, 39
	v_cndmask_b32_e64 v0, v0, v84, s[40:41]
	v_cndmask_b32_e64 v1, v1, v28, s[40:41]
	v_lshl_add_u64 v[2:3], v[2:3], 3, s[24:25]
	global_store_dwordx2 v[2:3], v[0:1], off
	s_branch .LBB0_61

.LBB0_1931:
	s_or_b64 exec, exec, s[20:21]
	s_mov_b64 s[20:21], exec
	v_mbcnt_lo_u32_b32 v0, s20, 0
	v_mbcnt_hi_u32_b32 v0, s21, v0
	v_cmp_eq_u32_e32 vcc, 0, v0
	s_waitcnt vmcnt(0)
	buffer_inv sc1
	s_and_saveexec_b64 s[28:29], vcc
	s_cbranch_execz .LBB0_1933
	s_bcnt1_i32_b64 s20, s[20:21]
	v_mov_b32_e32 v0, s20
	v_readlane_b32 s20, v233, 36
	v_readlane_b32 s21, v233, 37
	s_nop 4
.LBB0_1933:
	s_or_b64 exec, exec, s[28:29]
	s_waitcnt vmcnt(0)
